# P2b: spatial-gate GEMM epilogue store/load/wait chain turned into a 3-deep register-ring prefetch (incl. the per-row bias loads), on top of the P2 hand-written passes
# speedup vs baseline: 1.0076x; 1.0076x over previous
.LBB0_365:
	s_ashr_i32 s12, s76, 1
	v_mov_b32_e32 v129, v148
	v_mov_b32_e32 v128, v149
	s_and_b32 s52, s12, 0xffffff80
	s_cmp_lt_i32 s79, 1
	v_add_u32_e32 v155, s58, v129
	v_lshl_add_u32 v156, v128, 3, s59
	s_cbranch_scc1 .LBB0_369
	s_mov_b64 s[48:49], 0
	s_cmp_eq_u32 s79, 1
	s_mov_b64 s[50:51], 0
	s_cbranch_scc0 .LBB0_368
	v_add_u32_e32 v128, s52, v155
	v_ashrrev_i32_e32 v129, 31, v128
	v_add_u32_e32 v144, s76, v156
	v_add_u32_e32 v130, s75, v155
	s_waitcnt lgkmcnt(0)
	v_lshl_add_u64 v[128:129], v[128:129], 2, s[4:5]
	v_mov_b64_e32 v[146:147], s[14:15]
	v_ashrrev_i32_e32 v145, 31, v144
	global_load_dword v157, v[128:129], off
	v_mad_i64_i32 v[162:163], s[50:51], v130, s62, v[146:147]
	v_lshlrev_b64 v[128:129], 1, v[144:145]
	v_lshl_add_u64 v[158:159], v[162:163], 0, v[128:129]
	flat_load_dwordx4 v[158:161], v[158:159]
	v_ashrrev_i32_e32 v131, 31, v130
	v_add_u32_e32 v144, 0x80, v144
	v_lshlrev_b64 v[130:131], 12, v[130:131]
	v_ashrrev_i32_e32 v145, 31, v144
	v_lshl_add_u64 v[166:167], s[38:39], 0, v[130:131]
	v_lshlrev_b64 v[130:131], 1, v[144:145]
	v_lshl_add_u64 v[168:169], v[166:167], 0, v[128:129]
	v_lshl_add_u64 v[162:163], v[162:163], 0, v[130:131]
	global_load_dwordx4 v[236:239], v[162:163], off
	v_add_u32_e32 v176, 16, v155
	v_add_u32_e32 v178, s75, v176
	v_mad_i64_i32 v[180:181], s[50:51], v178, s62, v[146:147]
	v_lshl_add_u64 v[174:175], v[180:181], 0, v[128:129]
	global_load_dwordx4 v[244:247], v[174:175], off
	v_add_u32_e32 v184, 16, v155
	v_add_u32_e32 v182, s52, v184
	v_ashrrev_i32_e32 v183, 31, v182
	v_lshl_add_u64 v[182:183], v[182:183], 2, s[4:5]
	global_load_dword v248, v[182:183], off
	s_waitcnt vmcnt(3)
	v_add_u32_e32 v176, 16, v155
	v_add_u32_e32 v178, s75, v176
	v_mad_i64_i32 v[180:181], s[50:51], v178, s62, v[146:147]
	v_lshl_add_u64 v[174:175], v[180:181], 0, v[130:131]
	global_load_dwordx4 v[228:231], v[174:175], off
	v_add_f32_e32 v123, v123, v157
	v_add_f32_e32 v124, v124, v157
	v_add_f32_e32 v125, v125, v157
	v_add_f32_e32 v126, v126, v157
	v_add_f32_e32 v127, v127, v157
	s_waitcnt lgkmcnt(0)
	v_lshlrev_b32_e32 v173, 16, v161
	v_and_b32_e32 v161, 0xffff0000, v161
	v_add_f32_e32 v120, v120, v157
	v_add_f32_e32 v121, v121, v157
	v_add_f32_e32 v122, v122, v157
	v_lshlrev_b32_e32 v170, 16, v158
	v_and_b32_e32 v158, 0xffff0000, v158
	v_lshlrev_b32_e32 v171, 16, v159
	v_and_b32_e32 v159, 0xffff0000, v159
	v_lshlrev_b32_e32 v172, 16, v160
	v_and_b32_e32 v160, 0xffff0000, v160
	v_mul_f32_e32 v123, v123, v161
	v_mul_f32_e32 v124, v124, v170
	v_mul_f32_e32 v125, v125, v158
	v_mul_f32_e32 v126, v126, v171
	v_mul_f32_e32 v127, v127, v159
	v_mul_f32_e32 v158, v120, v172
	v_mul_f32_e32 v159, v121, v160
	v_mul_f32_e32 v160, v122, v173
	v_cvt_pk_bf16_f32 v120, v124, v125
	v_cvt_pk_bf16_f32 v121, v126, v127
	v_cvt_pk_bf16_f32 v122, v158, v159
	v_cvt_pk_bf16_f32 v123, v160, v123
	flat_store_dwordx4 v[168:169], v[120:123]
	v_add_f32_e32 v116, v116, v157
	v_add_f32_e32 v117, v117, v157
	v_add_f32_e32 v118, v118, v157
	v_add_f32_e32 v119, v119, v157
	v_add_f32_e32 v112, v112, v157
	v_add_f32_e32 v113, v113, v157
	v_add_f32_e32 v114, v114, v157
	v_add_f32_e32 v115, v115, v157
	v_add_u32_e32 v125, 16, v155
	v_add_u32_e32 v124, s75, v125
	v_lshl_add_u64 v[160:161], v[166:167], 0, v[130:131]
	v_mad_i64_i32 v[126:127], s[50:51], v124, s62, v[146:147]
	v_lshl_add_u64 v[158:159], v[126:127], 0, v[128:129]
	s_waitcnt vmcnt(4) lgkmcnt(0)
	s_nop 1
	v_mov_b32_e32 v120, v236
	v_mov_b32_e32 v121, v237
	v_mov_b32_e32 v122, v238
	v_mov_b32_e32 v123, v239
	v_add_u32_e32 v176, 32, v155
	v_add_u32_e32 v178, s75, v176
	v_mad_i64_i32 v[180:181], s[50:51], v178, s62, v[146:147]
	v_lshl_add_u64 v[174:175], v[180:181], 0, v[128:129]
	global_load_dwordx4 v[236:239], v[174:175], off
	v_add_u32_e32 v184, 32, v155
	v_add_u32_e32 v182, s52, v184
	v_ashrrev_i32_e32 v183, 31, v182
	v_lshl_add_u64 v[182:183], v[182:183], 2, s[4:5]
	global_load_dword v240, v[182:183], off
	v_lshlrev_b32_e32 v157, 16, v120
	v_and_b32_e32 v120, 0xffff0000, v120
	v_lshlrev_b32_e32 v163, 16, v122
	v_mul_f32_e32 v116, v116, v157
	v_lshlrev_b32_e32 v166, 16, v123
	v_and_b32_e32 v123, 0xffff0000, v123
	v_mul_f32_e32 v117, v117, v120
	v_mul_f32_e32 v120, v112, v163
	v_cvt_pk_bf16_f32 v112, v116, v117
	v_add_u32_e32 v116, s52, v125
	v_lshlrev_b32_e32 v162, 16, v121
	v_and_b32_e32 v121, 0xffff0000, v121
	v_and_b32_e32 v122, 0xffff0000, v122
	v_mul_f32_e32 v115, v115, v123
	v_ashrrev_i32_e32 v117, 31, v116
	v_mul_f32_e32 v118, v118, v162
	v_mul_f32_e32 v119, v119, v121
	v_mul_f32_e32 v121, v113, v122
	v_mul_f32_e32 v122, v114, v166
	v_cvt_pk_bf16_f32 v113, v118, v119
	v_cvt_pk_bf16_f32 v114, v120, v121
	v_cvt_pk_bf16_f32 v115, v122, v115
	flat_store_dwordx4 v[160:161], v[112:115]
	v_lshl_add_u64 v[116:117], v[116:117], 2, s[4:5]
	v_ashrrev_i32_e32 v125, 31, v124
	v_lshlrev_b64 v[116:117], 12, v[124:125]
	v_lshl_add_u64 v[116:117], s[38:39], 0, v[116:117]
	v_lshl_add_u64 v[118:119], v[126:127], 0, v[130:131]
	v_lshl_add_u64 v[120:121], v[116:117], 0, v[128:129]
	s_waitcnt vmcnt(5) lgkmcnt(0)
	s_nop 1
	v_mov_b32_e32 v112, v244
	v_mov_b32_e32 v113, v245
	v_mov_b32_e32 v114, v246
	v_mov_b32_e32 v115, v247
	v_mov_b32_e32 v122, v248
	v_add_u32_e32 v176, 32, v155
	v_add_u32_e32 v178, s75, v176
	v_mad_i64_i32 v[180:181], s[50:51], v178, s62, v[146:147]
	v_lshl_add_u64 v[174:175], v[180:181], 0, v[130:131]
	global_load_dwordx4 v[244:247], v[174:175], off
	v_lshlrev_b32_e32 v126, 16, v115
	v_and_b32_e32 v115, 0xffff0000, v115
	v_add_f32_e32 v107, v107, v122
	v_lshlrev_b32_e32 v123, 16, v112
	v_and_b32_e32 v112, 0xffff0000, v112
	v_lshlrev_b32_e32 v124, 16, v113
	v_and_b32_e32 v113, 0xffff0000, v113
	v_lshlrev_b32_e32 v125, 16, v114
	v_and_b32_e32 v114, 0xffff0000, v114
	v_add_f32_e32 v108, v108, v122
	v_add_f32_e32 v109, v109, v122
	v_add_f32_e32 v110, v110, v122
	v_add_f32_e32 v111, v111, v122
	v_add_f32_e32 v104, v104, v122
	v_add_f32_e32 v105, v105, v122
	v_add_f32_e32 v106, v106, v122
	v_mul_f32_e32 v107, v107, v115
	v_mul_f32_e32 v108, v108, v123
	v_mul_f32_e32 v109, v109, v112
	v_mul_f32_e32 v110, v110, v124
	v_mul_f32_e32 v111, v111, v113
	v_mul_f32_e32 v112, v104, v125
	v_mul_f32_e32 v113, v105, v114
	v_mul_f32_e32 v114, v106, v126
	v_cvt_pk_bf16_f32 v104, v108, v109
	v_cvt_pk_bf16_f32 v105, v110, v111
	v_cvt_pk_bf16_f32 v106, v112, v113
	v_cvt_pk_bf16_f32 v107, v114, v107
	flat_store_dwordx4 v[120:121], v[104:107]
	v_lshl_add_u64 v[114:115], v[116:117], 0, v[130:131]
	v_add_f32_e32 v100, v100, v122
	v_add_u32_e32 v109, 32, v155
	v_add_f32_e32 v101, v101, v122
	v_add_f32_e32 v96, v96, v122
	v_add_u32_e32 v108, s75, v109
	v_add_f32_e32 v99, v99, v122
	v_mad_i64_i32 v[110:111], s[50:51], v108, s62, v[146:147]
	v_add_f32_e32 v102, v102, v122
	v_add_f32_e32 v103, v103, v122
	v_add_f32_e32 v97, v97, v122
	v_add_f32_e32 v98, v98, v122
	v_lshl_add_u64 v[112:113], v[110:111], 0, v[128:129]
	s_waitcnt vmcnt(6) lgkmcnt(0)
	s_nop 1
	v_mov_b32_e32 v104, v228
	v_mov_b32_e32 v105, v229
	v_mov_b32_e32 v106, v230
	v_mov_b32_e32 v107, v231
	v_add_u32_e32 v176, 48, v155
	v_add_u32_e32 v178, s75, v176
	v_mad_i64_i32 v[180:181], s[50:51], v178, s62, v[146:147]
	v_lshl_add_u64 v[174:175], v[180:181], 0, v[128:129]
	global_load_dwordx4 v[228:231], v[174:175], off
	v_add_u32_e32 v184, 48, v155
	v_add_u32_e32 v182, s52, v184
	v_ashrrev_i32_e32 v183, 31, v182
	v_lshl_add_u64 v[182:183], v[182:183], 2, s[4:5]
	global_load_dword v232, v[182:183], off
	v_lshlrev_b32_e32 v116, 16, v104
	v_and_b32_e32 v104, 0xffff0000, v104
	v_lshlrev_b32_e32 v118, 16, v106
	v_mul_f32_e32 v100, v100, v116
	v_lshlrev_b32_e32 v119, 16, v107
	v_and_b32_e32 v107, 0xffff0000, v107
	v_mul_f32_e32 v101, v101, v104
	v_mul_f32_e32 v104, v96, v118
	v_cvt_pk_bf16_f32 v96, v100, v101
	v_add_u32_e32 v100, s52, v109
	v_lshlrev_b32_e32 v117, 16, v105
	v_and_b32_e32 v105, 0xffff0000, v105
	v_and_b32_e32 v106, 0xffff0000, v106
	v_mul_f32_e32 v99, v99, v107
	v_ashrrev_i32_e32 v101, 31, v100
	v_mul_f32_e32 v102, v102, v117
	v_mul_f32_e32 v103, v103, v105
	v_mul_f32_e32 v105, v97, v106
	v_mul_f32_e32 v106, v98, v119
	v_cvt_pk_bf16_f32 v97, v102, v103
	v_cvt_pk_bf16_f32 v98, v104, v105
	v_cvt_pk_bf16_f32 v99, v106, v99
	flat_store_dwordx4 v[114:115], v[96:99]
	v_lshl_add_u64 v[100:101], v[100:101], 2, s[4:5]
	v_ashrrev_i32_e32 v109, 31, v108
	v_lshlrev_b64 v[100:101], 12, v[108:109]
	v_lshl_add_u64 v[100:101], s[38:39], 0, v[100:101]
	v_lshl_add_u64 v[102:103], v[110:111], 0, v[130:131]
	v_lshl_add_u64 v[104:105], v[100:101], 0, v[128:129]
	s_waitcnt vmcnt(6) lgkmcnt(0)
	s_nop 1
	v_mov_b32_e32 v96, v236
	v_mov_b32_e32 v97, v237
	v_mov_b32_e32 v98, v238
	v_mov_b32_e32 v99, v239
	v_mov_b32_e32 v106, v240
	v_add_u32_e32 v176, 48, v155
	v_add_u32_e32 v178, s75, v176
	v_mad_i64_i32 v[180:181], s[50:51], v178, s62, v[146:147]
	v_lshl_add_u64 v[174:175], v[180:181], 0, v[130:131]
	global_load_dwordx4 v[236:239], v[174:175], off
	v_lshlrev_b32_e32 v110, 16, v99
	v_and_b32_e32 v99, 0xffff0000, v99
	v_add_f32_e32 v91, v91, v106
	v_lshlrev_b32_e32 v107, 16, v96
	v_and_b32_e32 v96, 0xffff0000, v96
	v_lshlrev_b32_e32 v108, 16, v97
	v_and_b32_e32 v97, 0xffff0000, v97
	v_lshlrev_b32_e32 v109, 16, v98
	v_and_b32_e32 v98, 0xffff0000, v98
	v_add_f32_e32 v92, v92, v106
	v_add_f32_e32 v93, v93, v106
	v_add_f32_e32 v94, v94, v106
	v_add_f32_e32 v95, v95, v106
	v_add_f32_e32 v88, v88, v106
	v_add_f32_e32 v89, v89, v106
	v_add_f32_e32 v90, v90, v106
	v_mul_f32_e32 v91, v91, v99
	v_mul_f32_e32 v92, v92, v107
	v_mul_f32_e32 v93, v93, v96
	v_mul_f32_e32 v94, v94, v108
	v_mul_f32_e32 v95, v95, v97
	v_mul_f32_e32 v96, v88, v109
	v_mul_f32_e32 v97, v89, v98
	v_mul_f32_e32 v98, v90, v110
	v_cvt_pk_bf16_f32 v88, v92, v93
	v_cvt_pk_bf16_f32 v89, v94, v95
	v_cvt_pk_bf16_f32 v90, v96, v97
	v_cvt_pk_bf16_f32 v91, v98, v91
	flat_store_dwordx4 v[104:105], v[88:91]
	v_lshl_add_u64 v[98:99], v[100:101], 0, v[130:131]
	v_add_f32_e32 v84, v84, v106
	v_add_u32_e32 v93, 48, v155
	v_add_f32_e32 v85, v85, v106
	v_add_f32_e32 v80, v80, v106
	v_add_u32_e32 v92, s75, v93
	v_add_f32_e32 v83, v83, v106
	v_mad_i64_i32 v[94:95], s[50:51], v92, s62, v[146:147]
	v_add_f32_e32 v86, v86, v106
	v_add_f32_e32 v87, v87, v106
	v_add_f32_e32 v81, v81, v106
	v_add_f32_e32 v82, v82, v106
	v_lshl_add_u64 v[96:97], v[94:95], 0, v[128:129]
	s_mov_b64 s[50:51], -1
	s_waitcnt vmcnt(6) lgkmcnt(0)
	s_nop 1
	v_mov_b32_e32 v88, v244
	v_mov_b32_e32 v89, v245
	v_mov_b32_e32 v90, v246
	v_mov_b32_e32 v91, v247
	v_lshlrev_b32_e32 v100, 16, v88
	v_and_b32_e32 v88, 0xffff0000, v88
	v_lshlrev_b32_e32 v102, 16, v90
	v_mul_f32_e32 v84, v84, v100
	v_lshlrev_b32_e32 v103, 16, v91
	v_and_b32_e32 v91, 0xffff0000, v91
	v_mul_f32_e32 v85, v85, v88
	v_mul_f32_e32 v88, v80, v102
	v_cvt_pk_bf16_f32 v80, v84, v85
	v_add_u32_e32 v84, s52, v93
	v_lshlrev_b32_e32 v101, 16, v89
	v_and_b32_e32 v89, 0xffff0000, v89
	v_and_b32_e32 v90, 0xffff0000, v90
	v_mul_f32_e32 v83, v83, v91
	v_ashrrev_i32_e32 v85, 31, v84
	v_mul_f32_e32 v86, v86, v101
	v_mul_f32_e32 v87, v87, v89
	v_mul_f32_e32 v89, v81, v90
	v_mul_f32_e32 v90, v82, v103
	v_cvt_pk_bf16_f32 v81, v86, v87
	v_cvt_pk_bf16_f32 v82, v88, v89
	v_cvt_pk_bf16_f32 v83, v90, v83
	flat_store_dwordx4 v[98:99], v[80:83]
	v_lshl_add_u64 v[84:85], v[84:85], 2, s[4:5]
	v_ashrrev_i32_e32 v93, 31, v92
	v_lshlrev_b64 v[146:147], 12, v[92:93]
	v_lshl_add_u64 v[84:85], s[38:39], 0, v[146:147]
	v_lshl_add_u64 v[84:85], v[84:85], 0, v[128:129]
	v_lshl_add_u64 v[86:87], v[94:95], 0, v[130:131]
	s_waitcnt vmcnt(4) lgkmcnt(0)
	s_nop 1
	v_mov_b32_e32 v80, v228
	v_mov_b32_e32 v81, v229
	v_mov_b32_e32 v82, v230
	v_mov_b32_e32 v83, v231
	v_mov_b32_e32 v88, v232
	v_lshlrev_b32_e32 v92, 16, v83
	v_and_b32_e32 v83, 0xffff0000, v83
	v_add_f32_e32 v75, v75, v88
	v_lshlrev_b32_e32 v89, 16, v80
	v_and_b32_e32 v80, 0xffff0000, v80
	v_lshlrev_b32_e32 v90, 16, v81
	v_and_b32_e32 v81, 0xffff0000, v81
	v_lshlrev_b32_e32 v91, 16, v82
	v_and_b32_e32 v82, 0xffff0000, v82
	v_add_f32_e32 v76, v76, v88
	v_add_f32_e32 v77, v77, v88
	v_add_f32_e32 v78, v78, v88
	v_add_f32_e32 v79, v79, v88
	v_add_f32_e32 v72, v72, v88
	v_add_f32_e32 v73, v73, v88
	v_add_f32_e32 v74, v74, v88
	v_mul_f32_e32 v75, v75, v83
	v_mul_f32_e32 v76, v76, v89
	v_mul_f32_e32 v77, v77, v80
	v_mul_f32_e32 v78, v78, v90
	v_mul_f32_e32 v79, v79, v81
	v_mul_f32_e32 v80, v72, v91
	v_mul_f32_e32 v81, v73, v82
	v_mul_f32_e32 v82, v74, v92
	v_cvt_pk_bf16_f32 v72, v76, v77
	v_cvt_pk_bf16_f32 v73, v78, v79
	v_cvt_pk_bf16_f32 v74, v80, v81
	v_cvt_pk_bf16_f32 v75, v82, v75
	flat_store_dwordx4 v[84:85], v[72:75]
	v_add_f32_e32 v68, v68, v88
	v_add_f32_e32 v69, v69, v88
	v_add_f32_e32 v70, v70, v88
	v_add_f32_e32 v71, v71, v88
	v_add_f32_e32 v64, v64, v88
	v_add_f32_e32 v65, v65, v88
	v_add_f32_e32 v66, v66, v88
	v_add_f32_e32 v67, v67, v88
	s_waitcnt vmcnt(3) lgkmcnt(0)
	s_nop 1
	v_mov_b32_e32 v72, v236
	v_mov_b32_e32 v73, v237
	v_mov_b32_e32 v74, v238
	v_mov_b32_e32 v75, v239
	v_lshlrev_b32_e32 v76, 16, v72
	v_and_b32_e32 v72, 0xffff0000, v72
	v_lshlrev_b32_e32 v77, 16, v73
	v_and_b32_e32 v73, 0xffff0000, v73
	v_lshlrev_b32_e32 v78, 16, v74
	v_and_b32_e32 v74, 0xffff0000, v74
	v_lshlrev_b32_e32 v79, 16, v75
	v_and_b32_e32 v75, 0xffff0000, v75
	v_mul_f32_e32 v68, v68, v76
	v_mul_f32_e32 v69, v69, v72
	v_mul_f32_e32 v70, v70, v77
	v_mul_f32_e32 v71, v71, v73
	v_mul_f32_e32 v64, v64, v78
	v_mul_f32_e32 v65, v65, v74
	v_mul_f32_e32 v66, v66, v79
	v_mul_f32_e32 v67, v67, v75
	v_cvt_pk_bf16_f32 v128, v68, v69
	v_cvt_pk_bf16_f32 v129, v70, v71
	v_cvt_pk_bf16_f32 v130, v64, v65
	v_cvt_pk_bf16_f32 v131, v66, v67

.LBB0_377:
	v_add_u32_e32 v64, s52, v155
	v_ashrrev_i32_e32 v65, 31, v64
	v_add_u32_e32 v74, s76, v156
	v_add_u32_e32 v66, s75, v155
	s_waitcnt lgkmcnt(0)
	v_lshl_add_u64 v[64:65], v[64:65], 2, s[4:5]
	v_mov_b64_e32 v[68:69], s[14:15]
	v_ashrrev_i32_e32 v75, 31, v74
	global_load_dword v80, v[64:65], off
	v_mad_i64_i32 v[76:77], s[48:49], v66, s62, v[68:69]
	v_lshlrev_b64 v[64:65], 1, v[74:75]
	v_lshl_add_u64 v[70:71], v[76:77], 0, v[64:65]
	flat_load_dwordx4 v[70:73], v[70:71]
	v_ashrrev_i32_e32 v67, 31, v66
	v_add_u32_e32 v144, 0x80, v74
	v_lshlrev_b64 v[66:67], 12, v[66:67]
	v_ashrrev_i32_e32 v145, 31, v144
	v_lshl_add_u64 v[74:75], s[38:39], 0, v[66:67]
	v_lshlrev_b64 v[66:67], 1, v[144:145]
	v_lshl_add_u64 v[78:79], v[74:75], 0, v[64:65]
	v_lshl_add_u64 v[76:77], v[76:77], 0, v[66:67]
	global_load_dwordx4 v[236:239], v[76:77], off
	v_add_u32_e32 v176, 16, v155
	v_add_u32_e32 v178, s75, v176
	v_mad_i64_i32 v[180:181], s[48:49], v178, s62, v[68:69]
	v_lshl_add_u64 v[174:175], v[180:181], 0, v[64:65]
	global_load_dwordx4 v[244:247], v[174:175], off
	v_add_u32_e32 v184, 16, v155
	v_add_u32_e32 v182, s52, v184
	v_ashrrev_i32_e32 v183, 31, v182
	v_lshl_add_u64 v[182:183], v[182:183], 2, s[4:5]
	global_load_dword v248, v[182:183], off
	s_waitcnt vmcnt(3)
	v_add_u32_e32 v176, 16, v155
	v_add_u32_e32 v178, s75, v176
	v_mad_i64_i32 v[180:181], s[48:49], v178, s62, v[68:69]
	v_lshl_add_u64 v[174:175], v[180:181], 0, v[66:67]
	global_load_dwordx4 v[228:231], v[174:175], off
	v_add_f32_e32 v59, v59, v80
	v_add_f32_e32 v60, v60, v80
	v_add_f32_e32 v61, v61, v80
	v_add_f32_e32 v62, v62, v80
	v_add_f32_e32 v63, v63, v80
	s_waitcnt lgkmcnt(0)
	v_lshlrev_b32_e32 v84, 16, v73
	v_and_b32_e32 v73, 0xffff0000, v73
	v_add_f32_e32 v56, v56, v80
	v_add_f32_e32 v57, v57, v80
	v_add_f32_e32 v58, v58, v80
	v_lshlrev_b32_e32 v81, 16, v70
	v_and_b32_e32 v70, 0xffff0000, v70
	v_lshlrev_b32_e32 v82, 16, v71
	v_and_b32_e32 v71, 0xffff0000, v71
	v_lshlrev_b32_e32 v83, 16, v72
	v_and_b32_e32 v72, 0xffff0000, v72
	v_mul_f32_e32 v59, v59, v73
	v_mul_f32_e32 v60, v60, v81
	v_mul_f32_e32 v61, v61, v70
	v_mul_f32_e32 v62, v62, v82
	v_mul_f32_e32 v63, v63, v71
	v_mul_f32_e32 v70, v56, v83
	v_mul_f32_e32 v71, v57, v72
	v_mul_f32_e32 v72, v58, v84
	v_cvt_pk_bf16_f32 v56, v60, v61
	v_cvt_pk_bf16_f32 v57, v62, v63
	v_cvt_pk_bf16_f32 v58, v70, v71
	v_cvt_pk_bf16_f32 v59, v72, v59
	flat_store_dwordx4 v[78:79], v[56:59]
	v_lshl_add_u64 v[72:73], v[74:75], 0, v[66:67]
	v_add_f32_e32 v52, v52, v80
	v_add_u32_e32 v61, 16, v155
	v_add_f32_e32 v53, v53, v80
	v_add_f32_e32 v48, v48, v80
	v_add_u32_e32 v60, s75, v61
	v_add_f32_e32 v51, v51, v80
	v_mad_i64_i32 v[62:63], s[48:49], v60, s62, v[68:69]
	v_add_f32_e32 v54, v54, v80
	v_add_f32_e32 v55, v55, v80
	v_add_f32_e32 v49, v49, v80
	v_add_f32_e32 v50, v50, v80
	v_lshl_add_u64 v[70:71], v[62:63], 0, v[64:65]
	s_waitcnt vmcnt(4) lgkmcnt(0)
	s_nop 1
	v_mov_b32_e32 v56, v236
	v_mov_b32_e32 v57, v237
	v_mov_b32_e32 v58, v238
	v_mov_b32_e32 v59, v239
	v_add_u32_e32 v176, 32, v155
	v_add_u32_e32 v178, s75, v176
	v_mad_i64_i32 v[180:181], s[48:49], v178, s62, v[68:69]
	v_lshl_add_u64 v[174:175], v[180:181], 0, v[64:65]
	global_load_dwordx4 v[236:239], v[174:175], off
	v_add_u32_e32 v184, 32, v155
	v_add_u32_e32 v182, s52, v184
	v_ashrrev_i32_e32 v183, 31, v182
	v_lshl_add_u64 v[182:183], v[182:183], 2, s[4:5]
	global_load_dword v240, v[182:183], off
	v_lshlrev_b32_e32 v74, 16, v56
	v_and_b32_e32 v56, 0xffff0000, v56
	v_lshlrev_b32_e32 v76, 16, v58
	v_mul_f32_e32 v52, v52, v74
	v_lshlrev_b32_e32 v77, 16, v59
	v_and_b32_e32 v59, 0xffff0000, v59
	v_mul_f32_e32 v53, v53, v56
	v_mul_f32_e32 v56, v48, v76
	v_cvt_pk_bf16_f32 v48, v52, v53
	v_add_u32_e32 v52, s52, v61
	v_lshlrev_b32_e32 v75, 16, v57
	v_and_b32_e32 v57, 0xffff0000, v57
	v_and_b32_e32 v58, 0xffff0000, v58
	v_mul_f32_e32 v51, v51, v59
	v_ashrrev_i32_e32 v53, 31, v52
	v_mul_f32_e32 v54, v54, v75
	v_mul_f32_e32 v55, v55, v57
	v_mul_f32_e32 v57, v49, v58
	v_mul_f32_e32 v58, v50, v77
	v_cvt_pk_bf16_f32 v49, v54, v55
	v_cvt_pk_bf16_f32 v50, v56, v57
	v_cvt_pk_bf16_f32 v51, v58, v51
	flat_store_dwordx4 v[72:73], v[48:51]
	v_lshl_add_u64 v[52:53], v[52:53], 2, s[4:5]
	v_ashrrev_i32_e32 v61, 31, v60
	v_lshlrev_b64 v[52:53], 12, v[60:61]
	v_lshl_add_u64 v[52:53], s[38:39], 0, v[52:53]
	v_lshl_add_u64 v[54:55], v[62:63], 0, v[66:67]
	v_lshl_add_u64 v[56:57], v[52:53], 0, v[64:65]
	s_waitcnt vmcnt(5) lgkmcnt(0)
	s_nop 1
	v_mov_b32_e32 v48, v244
	v_mov_b32_e32 v49, v245
	v_mov_b32_e32 v50, v246
	v_mov_b32_e32 v51, v247
	v_mov_b32_e32 v58, v248
	v_add_u32_e32 v176, 32, v155
	v_add_u32_e32 v178, s75, v176
	v_mad_i64_i32 v[180:181], s[48:49], v178, s62, v[68:69]
	v_lshl_add_u64 v[174:175], v[180:181], 0, v[66:67]
	global_load_dwordx4 v[244:247], v[174:175], off
	v_lshlrev_b32_e32 v62, 16, v51
	v_and_b32_e32 v51, 0xffff0000, v51
	v_add_f32_e32 v43, v43, v58
	v_lshlrev_b32_e32 v59, 16, v48
	v_and_b32_e32 v48, 0xffff0000, v48
	v_lshlrev_b32_e32 v60, 16, v49
	v_and_b32_e32 v49, 0xffff0000, v49
	v_lshlrev_b32_e32 v61, 16, v50
	v_and_b32_e32 v50, 0xffff0000, v50
	v_add_f32_e32 v44, v44, v58
	v_add_f32_e32 v45, v45, v58
	v_add_f32_e32 v46, v46, v58
	v_add_f32_e32 v47, v47, v58
	v_add_f32_e32 v40, v40, v58
	v_add_f32_e32 v41, v41, v58
	v_add_f32_e32 v42, v42, v58
	v_mul_f32_e32 v43, v43, v51
	v_mul_f32_e32 v44, v44, v59
	v_mul_f32_e32 v45, v45, v48
	v_mul_f32_e32 v46, v46, v60
	v_mul_f32_e32 v47, v47, v49
	v_mul_f32_e32 v48, v40, v61
	v_mul_f32_e32 v49, v41, v50
	v_mul_f32_e32 v50, v42, v62
	v_cvt_pk_bf16_f32 v40, v44, v45
	v_cvt_pk_bf16_f32 v41, v46, v47
	v_cvt_pk_bf16_f32 v42, v48, v49
	v_cvt_pk_bf16_f32 v43, v50, v43
	flat_store_dwordx4 v[56:57], v[40:43]
	v_lshl_add_u64 v[50:51], v[52:53], 0, v[66:67]
	v_add_f32_e32 v36, v36, v58
	v_add_u32_e32 v45, 32, v155
	v_add_f32_e32 v37, v37, v58
	v_add_f32_e32 v32, v32, v58
	v_add_u32_e32 v44, s75, v45
	v_add_f32_e32 v35, v35, v58
	v_mad_i64_i32 v[46:47], s[48:49], v44, s62, v[68:69]
	v_add_f32_e32 v38, v38, v58
	v_add_f32_e32 v39, v39, v58
	v_add_f32_e32 v33, v33, v58
	v_add_f32_e32 v34, v34, v58
	v_lshl_add_u64 v[48:49], v[46:47], 0, v[64:65]
	s_waitcnt vmcnt(6) lgkmcnt(0)
	s_nop 1
	v_mov_b32_e32 v40, v228
	v_mov_b32_e32 v41, v229
	v_mov_b32_e32 v42, v230
	v_mov_b32_e32 v43, v231
	v_add_u32_e32 v176, 48, v155
	v_add_u32_e32 v178, s75, v176
	v_mad_i64_i32 v[180:181], s[48:49], v178, s62, v[68:69]
	v_lshl_add_u64 v[174:175], v[180:181], 0, v[64:65]
	global_load_dwordx4 v[228:231], v[174:175], off
	v_add_u32_e32 v184, 48, v155
	v_add_u32_e32 v182, s52, v184
	v_ashrrev_i32_e32 v183, 31, v182
	v_lshl_add_u64 v[182:183], v[182:183], 2, s[4:5]
	global_load_dword v232, v[182:183], off
	v_lshlrev_b32_e32 v52, 16, v40
	v_and_b32_e32 v40, 0xffff0000, v40
	v_lshlrev_b32_e32 v54, 16, v42
	v_mul_f32_e32 v36, v36, v52
	v_lshlrev_b32_e32 v55, 16, v43
	v_and_b32_e32 v43, 0xffff0000, v43
	v_mul_f32_e32 v37, v37, v40
	v_mul_f32_e32 v40, v32, v54
	v_cvt_pk_bf16_f32 v32, v36, v37
	v_add_u32_e32 v36, s52, v45
	v_lshlrev_b32_e32 v53, 16, v41
	v_and_b32_e32 v41, 0xffff0000, v41
	v_and_b32_e32 v42, 0xffff0000, v42
	v_mul_f32_e32 v35, v35, v43
	v_ashrrev_i32_e32 v37, 31, v36
	v_mul_f32_e32 v38, v38, v53
	v_mul_f32_e32 v39, v39, v41
	v_mul_f32_e32 v41, v33, v42
	v_mul_f32_e32 v42, v34, v55
	v_cvt_pk_bf16_f32 v33, v38, v39
	v_cvt_pk_bf16_f32 v34, v40, v41
	v_cvt_pk_bf16_f32 v35, v42, v35
	flat_store_dwordx4 v[50:51], v[32:35]
	v_lshl_add_u64 v[36:37], v[36:37], 2, s[4:5]
	v_ashrrev_i32_e32 v45, 31, v44
	v_lshlrev_b64 v[36:37], 12, v[44:45]
	v_lshl_add_u64 v[36:37], s[38:39], 0, v[36:37]
	v_lshl_add_u64 v[38:39], v[46:47], 0, v[66:67]
	v_lshl_add_u64 v[40:41], v[36:37], 0, v[64:65]
	s_waitcnt vmcnt(6) lgkmcnt(0)
	s_nop 1
	v_mov_b32_e32 v32, v236
	v_mov_b32_e32 v33, v237
	v_mov_b32_e32 v34, v238
	v_mov_b32_e32 v35, v239
	v_mov_b32_e32 v42, v240
	v_add_u32_e32 v176, 48, v155
	v_add_u32_e32 v178, s75, v176
	v_mad_i64_i32 v[180:181], s[48:49], v178, s62, v[68:69]
	v_lshl_add_u64 v[174:175], v[180:181], 0, v[66:67]
	global_load_dwordx4 v[236:239], v[174:175], off
	v_lshlrev_b32_e32 v46, 16, v35
	v_and_b32_e32 v35, 0xffff0000, v35
	v_add_f32_e32 v27, v27, v42
	v_lshlrev_b32_e32 v43, 16, v32
	v_and_b32_e32 v32, 0xffff0000, v32
	v_lshlrev_b32_e32 v44, 16, v33
	v_and_b32_e32 v33, 0xffff0000, v33
	v_lshlrev_b32_e32 v45, 16, v34
	v_and_b32_e32 v34, 0xffff0000, v34
	v_add_f32_e32 v28, v28, v42
	v_add_f32_e32 v29, v29, v42
	v_add_f32_e32 v30, v30, v42
	v_add_f32_e32 v31, v31, v42
	v_add_f32_e32 v24, v24, v42
	v_add_f32_e32 v25, v25, v42
	v_add_f32_e32 v26, v26, v42
	v_mul_f32_e32 v27, v27, v35
	v_mul_f32_e32 v28, v28, v43
	v_mul_f32_e32 v29, v29, v32
	v_mul_f32_e32 v30, v30, v44
	v_mul_f32_e32 v31, v31, v33
	v_mul_f32_e32 v32, v24, v45
	v_mul_f32_e32 v33, v25, v34
	v_mul_f32_e32 v34, v26, v46
	v_cvt_pk_bf16_f32 v24, v28, v29
	v_cvt_pk_bf16_f32 v25, v30, v31
	v_cvt_pk_bf16_f32 v26, v32, v33
	v_cvt_pk_bf16_f32 v27, v34, v27
	flat_store_dwordx4 v[40:41], v[24:27]
	v_lshl_add_u64 v[34:35], v[36:37], 0, v[66:67]
	v_add_f32_e32 v20, v20, v42
	v_add_u32_e32 v29, 48, v155
	v_add_f32_e32 v21, v21, v42
	v_add_f32_e32 v16, v16, v42
	v_add_u32_e32 v28, s75, v29
	v_add_f32_e32 v19, v19, v42
	v_mad_i64_i32 v[30:31], s[48:49], v28, s62, v[68:69]
	v_add_f32_e32 v22, v22, v42
	v_add_f32_e32 v23, v23, v42
	v_add_f32_e32 v17, v17, v42
	v_add_f32_e32 v18, v18, v42
	v_lshl_add_u64 v[32:33], v[30:31], 0, v[64:65]
	s_waitcnt vmcnt(6) lgkmcnt(0)
	s_nop 1
	v_mov_b32_e32 v24, v244
	v_mov_b32_e32 v25, v245
	v_mov_b32_e32 v26, v246
	v_mov_b32_e32 v27, v247
	v_lshlrev_b32_e32 v36, 16, v24
	v_and_b32_e32 v24, 0xffff0000, v24
	v_lshlrev_b32_e32 v38, 16, v26
	v_mul_f32_e32 v20, v20, v36
	v_lshlrev_b32_e32 v39, 16, v27
	v_and_b32_e32 v27, 0xffff0000, v27
	v_mul_f32_e32 v21, v21, v24
	v_mul_f32_e32 v24, v16, v38
	v_cvt_pk_bf16_f32 v16, v20, v21
	v_add_u32_e32 v20, s52, v29
	v_lshlrev_b32_e32 v37, 16, v25
	v_and_b32_e32 v25, 0xffff0000, v25
	v_and_b32_e32 v26, 0xffff0000, v26
	v_mul_f32_e32 v19, v19, v27
	v_ashrrev_i32_e32 v21, 31, v20
	v_mul_f32_e32 v22, v22, v37
	v_mul_f32_e32 v23, v23, v25
	v_mul_f32_e32 v25, v17, v26
	v_mul_f32_e32 v26, v18, v39
	v_cvt_pk_bf16_f32 v17, v22, v23
	v_cvt_pk_bf16_f32 v18, v24, v25
	v_cvt_pk_bf16_f32 v19, v26, v19
	flat_store_dwordx4 v[34:35], v[16:19]
	v_lshl_add_u64 v[20:21], v[20:21], 2, s[4:5]
	v_ashrrev_i32_e32 v29, 31, v28
	v_lshlrev_b64 v[146:147], 12, v[28:29]
	v_lshl_add_u64 v[20:21], s[38:39], 0, v[146:147]
	v_lshl_add_u64 v[20:21], v[20:21], 0, v[64:65]
	v_lshl_add_u64 v[22:23], v[30:31], 0, v[66:67]
	s_waitcnt vmcnt(4) lgkmcnt(0)
	s_nop 1
	v_mov_b32_e32 v16, v228
	v_mov_b32_e32 v17, v229
	v_mov_b32_e32 v18, v230
	v_mov_b32_e32 v19, v231
	v_mov_b32_e32 v24, v232
	v_lshlrev_b32_e32 v28, 16, v19
	v_and_b32_e32 v19, 0xffff0000, v19
	v_add_f32_e32 v11, v11, v24
	v_lshlrev_b32_e32 v25, 16, v16
	v_and_b32_e32 v16, 0xffff0000, v16
	v_lshlrev_b32_e32 v26, 16, v17
	v_and_b32_e32 v17, 0xffff0000, v17
	v_lshlrev_b32_e32 v27, 16, v18
	v_and_b32_e32 v18, 0xffff0000, v18
	v_add_f32_e32 v12, v12, v24
	v_add_f32_e32 v13, v13, v24
	v_add_f32_e32 v14, v14, v24
	v_add_f32_e32 v15, v15, v24
	v_add_f32_e32 v8, v8, v24
	v_add_f32_e32 v9, v9, v24
	v_add_f32_e32 v10, v10, v24
	v_mul_f32_e32 v11, v11, v19
	v_mul_f32_e32 v12, v12, v25
	v_mul_f32_e32 v13, v13, v16
	v_mul_f32_e32 v14, v14, v26
	v_mul_f32_e32 v15, v15, v17
	v_mul_f32_e32 v16, v8, v27
	v_mul_f32_e32 v17, v9, v18
	v_mul_f32_e32 v18, v10, v28
	v_cvt_pk_bf16_f32 v8, v12, v13
	v_cvt_pk_bf16_f32 v9, v14, v15
	v_cvt_pk_bf16_f32 v10, v16, v17
	v_cvt_pk_bf16_f32 v11, v18, v11
	flat_store_dwordx4 v[20:21], v[8:11]
	v_add_f32_e32 v4, v4, v24
	v_add_f32_e32 v5, v5, v24
	v_add_f32_e32 v6, v6, v24
	v_add_f32_e32 v7, v7, v24
	v_add_f32_e32 v0, v0, v24
	v_add_f32_e32 v1, v1, v24
	v_add_f32_e32 v2, v2, v24
	v_add_f32_e32 v3, v3, v24
	s_waitcnt vmcnt(3) lgkmcnt(0)
	s_nop 1
	v_mov_b32_e32 v8, v236
	v_mov_b32_e32 v9, v237
	v_mov_b32_e32 v10, v238
	v_mov_b32_e32 v11, v239
	v_lshlrev_b32_e32 v12, 16, v8
	v_and_b32_e32 v8, 0xffff0000, v8
	v_lshlrev_b32_e32 v13, 16, v9
	v_and_b32_e32 v9, 0xffff0000, v9
	v_lshlrev_b32_e32 v14, 16, v10
	v_and_b32_e32 v10, 0xffff0000, v10
	v_lshlrev_b32_e32 v15, 16, v11
	v_and_b32_e32 v11, 0xffff0000, v11
	v_mul_f32_e32 v4, v4, v12
	v_mul_f32_e32 v5, v5, v8
	v_mul_f32_e32 v6, v6, v13
	v_mul_f32_e32 v7, v7, v9
	v_mul_f32_e32 v0, v0, v14
	v_mul_f32_e32 v1, v1, v10
	v_mul_f32_e32 v2, v2, v15
	v_mul_f32_e32 v3, v3, v11
	v_cvt_pk_bf16_f32 v128, v4, v5
	v_cvt_pk_bf16_f32 v129, v6, v7
	v_cvt_pk_bf16_f32 v130, v0, v1
	v_cvt_pk_bf16_f32 v131, v2, v3
	s_cbranch_execnz .LBB0_372
	s_branch .LBB0_373
